# DA loop: packing of P deferred into next tile's QK1 MFMA shadows, next-tile K prefetch issued inside first PV gaps, leaner scalar loop control and rescale test, dead waits removed
# speedup vs baseline: 1.0243x; 1.0243x over previous
; __device__ __forceinline__ void da_phase(LAS unsigned char* lds, const bf16* Q, const bf16* Kb, const bf16* Vb, bf16* O, const float* lq1, const float* lk1, const float* lq2, const float* lk2,
;                                          const float* t5, int G, int wave, int lane, int tid) {
;     ...
;         const int qrow0 = qb * 128 + 32 * w4;
;         H8 qf[4];
; #pragma unroll
;         for (int d0 = 0; d0 < 4; ++d0) qf[d0] = *(const GASP H8*)(Q + ((size_t)h * T + tok0 + qrow0 + r32) * 128 + comp * 64 + 16 * d0 + 8 * hi);
;         float m = 0.f, l = 0.f; F16 o[4];
; #pragma unroll
;         for (int db = 0; db < 4; ++db) o[db] = F16{};
;         int cur_cls = -1; float cb = 0.f, cbm = 0.f;
;         U4 pw[4] = {};
;         const int NT = S / 64;
;         const char* kub = (const char*)Kb + (((size_t)h * T + tok0 + 32 * (wave & 1)) * 128 + (wave >> 2) * 64 + ((wave >> 1) & 1) * 32) * 2;
;         const char* vub = (const char*)Vb + (((size_t)h * T + tok0 + 16 * ((2 * wave) & 3)) * 128 + ((2 * wave) >> 2) * 32) * 2;
;         const unsigned kofs = (unsigned)(((lane >> 2) * 128 + ((lane & 3) ^ ((lane >> 4) & 3)) * 8) * 2);
;         const unsigned vofs = (unsigned)(((lane >> 2) * 128 + (lane & 3) * 8) * 2);
;     ...
;         DA_DMA(0, 0, 0); DA_DMA(1, 1, 1);
;         int ks_cur = 0, ks_n2 = 2;
;         const unsigned kswz = (unsigned)((hi ^ ((r32 >> 2) & 3)) * 16);
;         const unsigned ka_base = ldsb + KS + comp * 8192 + r32 * 64;
;         S4 va[8], vb[8];
; #pragma unroll 1
;         for (int t = 0; t < NT; ++t) {
;             if (t + 1 < NT) asm volatile("s_waitcnt vmcnt(4)" ::: "memory"); else asm volatile("s_waitcnt vmcnt(0)" ::: "memory");
;             __builtin_amdgcn_s_barrier();
;             asm volatile("" ::: "memory");
;             const unsigned vaddr_p = ldsb + VS + ((t == 0 ? 0 : t + 3) & 3) * 16384 + vlane;
;             U4 kf[4];
;             const unsigned ka0 = ka_base + ks_cur * 16384 + kswz, ka1 = ka_base + ks_cur * 16384 + (kswz ^ 32u);
;             DS_RD128(kf[0], ka0, 0); DS_RD128(kf[1], ka1, 0); DS_RD128(kf[2], ka0, 4096); DS_RD128(kf[3], ka1, 4096);
;             DA_VREADS(va, vaddr_p, 0); DA_VREADS(vb, vaddr_p, 1);
;             const int kv0 = 64 * t; const int relmin = kv0 - (qrow0 + 31), relmax = kv0 + 63 - qrow0;
;             const int cls = 1 + (relmin >= 128 ? 1 : 0) - (relmax <= -128 ? 1 : 0);
.LBB0_201:
	s_lshl_b32 s18, s38, 7
	v_readlane_b32 s0, v254, 47
	s_or_b32 s38, s18, s0
	s_mul_i32 s10, s36, 0x18000
	s_add_u32 s0, s10, s38
	s_addc_u32 s1, 0, 0
	s_add_u32 s0, s0, s14
	s_addc_u32 s1, s1, s15
	v_lshl_add_u64 v[2:3], s[0:1], 0, v[188:189]
	v_readlane_b32 s0, v254, 20
	s_add_u32 s0, s14, s0
	s_addc_u32 s1, s15, 0
	s_add_u32 s0, s0, s10
	s_addc_u32 s1, s1, 0
	s_lshl_b64 s[0:1], s[0:1], 8
	v_lshlrev_b64 v[2:3], 8, v[2:3]
	s_add_u32 s10, s34, s0
	v_lshl_add_u64 v[2:3], v[192:193], 0, v[2:3]
	s_addc_u32 s11, s35, s1
	s_mov_b32 m0, s3
	global_load_dwordx4 v[120:123], v[2:3], off
	global_load_dwordx4 v[124:127], v[2:3], off offset:32
	global_load_dwordx4 v[128:131], v[2:3], off offset:64
	global_load_dwordx4 v[132:135], v[2:3], off offset:96
	s_add_u32 s16, s30, s0
	v_lshl_add_u64 v[2:3], s[10:11], 0, v[194:195]
	s_addc_u32 s17, s31, s1
	global_load_lds_dwordx4 v[2:3], off
	v_lshl_add_u64 v[4:5], v[2:3], 0, s[62:63]
	s_add_i32 m0, s3, 0x400
	s_mov_b64 s[10:11], 0x4000
	global_load_lds_dwordx4 v[4:5], off
	v_lshl_add_u64 v[4:5], s[16:17], 0, v[196:197]
	s_add_i32 m0, s3, 0xc000
	v_lshl_add_u64 v[6:7], v[4:5], 0, s[62:63]
	global_load_lds_dwordx4 v[4:5], off
	s_add_i32 m0, s3, 0xc400
	s_mov_b64 s[16:17], 0x5000
	global_load_lds_dwordx4 v[6:7], off
	v_lshl_add_u64 v[6:7], v[2:3], 0, s[10:11]
	s_add_i32 m0, s3, 0x4000
	v_lshl_add_u64 v[2:3], v[2:3], 0, s[16:17]
	global_load_lds_dwordx4 v[6:7], off
	s_add_i32 m0, s3, 0x4400
	v_add_u32_e32 v0, s18, v228
	global_load_lds_dwordx4 v[2:3], off
	v_lshl_add_u64 v[2:3], v[4:5], 0, s[10:11]
	s_add_i32 s10, 0, 0x10000
	v_readlane_b32 s11, v254, 22
	s_add_i32 m0, s10, s11
	v_readlane_b32 s11, v254, 23
	v_lshl_add_u64 v[2:3], v[4:5], 0, s[16:17]
	s_add_i32 m0, s10, s11
	v_mov_b32_e32 v14, v1
	v_mov_b32_e32 v15, v1
	v_lshl_add_u64 v[202:203], v[198:199], 0, s[0:1]
	v_lshl_add_u64 v[204:205], v[200:201], 0, s[0:1]
	v_sub_u32_e32 v231, v219, v0
	v_readlane_b32 s0, v254, 48
	v_mov_b32_e32 v0, v1
	v_mov_b32_e32 v2, v1
	v_mov_b32_e32 v3, v1
	v_mov_b32_e32 v4, v1
	v_mov_b32_e32 v5, v1
	v_mov_b32_e32 v6, v1
	v_mov_b32_e32 v7, v1
	v_mov_b32_e32 v8, v1
	v_mov_b32_e32 v9, v1
	v_mov_b32_e32 v10, v1
	v_mov_b32_e32 v11, v1
	v_mov_b32_e32 v12, v1
	v_mov_b32_e32 v13, v1
	v_mov_b64_e32 v[30:31], v[14:15]
	v_mov_b64_e32 v[46:47], v[14:15]
	v_mov_b64_e32 v[62:63], v[14:15]
	v_mov_b64_e32 v[78:79], v[14:15]
	v_subrev_u32_e32 v230, s18, v227
	s_sub_i32 s40, s0, s18
	s_lshl_b32 s41, s39, 6
	s_mov_b32 s44, 0
	s_mov_b32 s50, -1
	v_mov_b32_e32 v232, 0
	s_mov_b64 s[16:17], 0
	s_mov_b32 s45, 2
	v_mov_b32_e32 v112, 0
	v_mov_b32_e32 v113, 0
	v_mov_b32_e32 v114, 0
	v_mov_b32_e32 v115, 0
	v_mov_b32_e32 v116, 0
	v_mov_b32_e32 v117, 0
	v_mov_b32_e32 v118, 0
	v_mov_b32_e32 v119, 0
	v_mov_b32_e32 v136, 0
	v_mov_b32_e32 v137, 0
	v_mov_b32_e32 v138, 0
	v_mov_b32_e32 v139, 0
	v_mov_b32_e32 v140, 0
	v_mov_b32_e32 v141, 0
	v_mov_b32_e32 v142, 0
	v_mov_b32_e32 v143, 0
	v_mov_b64_e32 v[28:29], v[12:13]
	v_mov_b64_e32 v[26:27], v[10:11]
	v_mov_b64_e32 v[24:25], v[8:9]
	v_mov_b64_e32 v[22:23], v[6:7]
	v_mov_b64_e32 v[20:21], v[4:5]
	v_mov_b64_e32 v[18:19], v[2:3]
	v_mov_b64_e32 v[16:17], v[0:1]
	v_mov_b64_e32 v[44:45], v[12:13]
	v_mov_b64_e32 v[42:43], v[10:11]
	v_mov_b64_e32 v[40:41], v[8:9]
	v_mov_b64_e32 v[38:39], v[6:7]
	v_mov_b64_e32 v[36:37], v[4:5]
	v_mov_b64_e32 v[34:35], v[2:3]
	v_mov_b64_e32 v[32:33], v[0:1]
	v_mov_b64_e32 v[60:61], v[12:13]
	v_mov_b64_e32 v[58:59], v[10:11]
	v_mov_b64_e32 v[56:57], v[8:9]
	v_mov_b64_e32 v[54:55], v[6:7]
	v_mov_b64_e32 v[52:53], v[4:5]
	v_mov_b64_e32 v[50:51], v[2:3]
	v_mov_b64_e32 v[48:49], v[0:1]
	v_mov_b64_e32 v[76:77], v[12:13]
	v_mov_b64_e32 v[74:75], v[10:11]
	v_mov_b64_e32 v[72:73], v[8:9]
	v_mov_b64_e32 v[70:71], v[6:7]
	v_mov_b64_e32 v[68:69], v[4:5]
	v_mov_b64_e32 v[66:67], v[2:3]
	v_mov_b64_e32 v[64:65], v[0:1]
	v_mov_b32_e32 v229, 0
	v_mov_b32_e32 v233, 0
	v_mov_b32_e32 v14, 0
	s_mov_b32 s46, 0
	s_mov_b32 s47, 2
	s_waitcnt vmcnt(0)
	s_barrier
	s_mov_b32 s18, 0xff800000
	s_mov_b32 s21, 0
	v_add_u32_e32 v253, v216, v191
	v_add_u32_e32 v252, v216, v218
	ds_read_b128 v[172:175], v253
	ds_read_b128 v[176:179], v252
	ds_read_b128 v[168:171], v253 offset:4096
	ds_read_b128 v[164:167], v252 offset:4096
	s_waitcnt lgkmcnt(0)
	v_mov_b32_e32 v0, 0
	v_mov_b32_e32 v2, 0
	v_mov_b32_e32 v3, 0
	v_mov_b32_e32 v5, 0
	v_mov_b32_e32 v6, 0
	v_mov_b32_e32 v7, 0
	v_mov_b32_e32 v8, 0
	v_mov_b32_e32 v9, 0
	v_mov_b32_e32 v10, 0
	v_mov_b32_e32 v15, 0
	v_mov_b32_e32 v80, 0
	v_mov_b32_e32 v81, 0
	v_mov_b32_e32 v82, 0
	v_mov_b32_e32 v83, 0
	v_mov_b32_e32 v84, 0
	v_mov_b32_e32 v85, 0
	v_mov_b32_e32 v86, 0
	v_mov_b32_e32 v87, 0
	v_mov_b32_e32 v108, 0
	v_mov_b32_e32 v109, 0
	v_mov_b32_e32 v110, 0
	v_mov_b32_e32 v111, 0
	v_mov_b32_e32 v144, 0
	v_mov_b32_e32 v145, 0
	v_mov_b32_e32 v146, 0
	v_mov_b32_e32 v147, 0
	v_mov_b32_e32 v156, 0
	v_mov_b32_e32 v157, 0
	v_mov_b32_e32 v158, 0
	v_mov_b32_e32 v159, 0
	v_mov_b32_e32 v160, 0
	v_mov_b32_e32 v161, 0
	s_branch .LBB0_204
.Lda_vskip:
	s_nop 3
	s_branch .LBB0_219

; #define DS_RD128(dst, addr, off) asm volatile("ds_read_b128 %0, %1 offset:%c2" : "=v"(dst) : "v"(addr), "i"(off) : "memory")
; #define LGKM_WAIT(n) asm volatile("s_waitcnt lgkmcnt(" #n ")" ::: "memory")
; #define SCHED_FENCE() __builtin_amdgcn_sched_barrier(0)
; #define DA_GROUP(v, DB, P, B, acc) do { DA_GAP(v, DB, 0, P, (B), acc); DA_GAP(v, DB, 1, P, (B) + 2, acc); DA_GAP(v, DB, 2, P, (B) + 4, acc); DA_GAP(v, DB, 3, P, (B) + 6, acc); } while (0)
; __device__ __forceinline__ void da_phase(LAS unsigned char* lds, const bf16* Q, const bf16* Kb, const bf16* Vb, bf16* O, const float* lq1, const float* lk1, const float* lq2, const float* lk2,
;                                          const float* t5, int G, int wave, int lane, int tid) {
;     ...
;         for (int t = 0; t < NT; ++t) {
;             if (t + 1 < NT) asm volatile("s_waitcnt vmcnt(4)" ::: "memory"); else asm volatile("s_waitcnt vmcnt(0)" ::: "memory");
;             __builtin_amdgcn_s_barrier();
;             asm volatile("" ::: "memory");
;             const unsigned vaddr_p = ldsb + VS + ((t == 0 ? 0 : t + 3) & 3) * 16384 + vlane;
;             U4 kf[4];
;             const unsigned ka0 = ka_base + ks_cur * 16384 + kswz, ka1 = ka_base + ks_cur * 16384 + (kswz ^ 32u);
;             DS_RD128(kf[0], ka0, 0); DS_RD128(kf[1], ka1, 0); DS_RD128(kf[2], ka0, 4096); DS_RD128(kf[3], ka1, 4096);
;             DA_VREADS(va, vaddr_p, 0); DA_VREADS(vb, vaddr_p, 1);
;             const int kv0 = 64 * t; const int relmin = kv0 - (qrow0 + 31), relmax = kv0 + 63 - qrow0;
;             const int cls = 1 + (relmin >= 128 ? 1 : 0) - (relmax <= -128 ? 1 : 0);
;             if (cls != cur_cls) { cur_cls = cls; cb = (cls == 2) ? lut[256] : ((cls == 0) ? lut[0] : 0.f); cbm = cb - m; }
;     ...
;             float sa = 0.f, sb = 0.f;
;             SCHED_FENCE(); DA_GROUP(va, 0, p0, 0, sa);
;             DA_VREADS(va, vaddr_p, 2); SCHED_FENCE();
;             DA_GROUP(vb, 1, p0, 8, sa);
;             DA_VREADS(vb, vaddr_p, 3); LGKM_WAIT(8); SCHED_FENCE();
;             DA_GROUP(va, 2, p1, 0, sa);
;             LGKM_WAIT(0); SCHED_FENCE();
;             DA_GROUP(vb, 3, p1, 8, sa);
;             l += sa + sb;
;             pw[0] = DA_PACK8(p0, 0); pw[1] = DA_PACK8(p0, 8); pw[2] = DA_PACK8(p1, 0); pw[3] = DA_PACK8(p1, 8);
;             ks_cur = (ks_cur == 2) ? 0 : ks_cur + 1; ks_n2 = (ks_n2 == 2) ? 0 : ks_n2 + 1;
.Lda_mid_bar:
	s_barrier
	v_mfma_f32_32x32x16_bf16 v[64:79], v[140:143], v[160:163], v[64:79]
	v_exp_f32_e32 v0, v96
	v_exp_f32_e32 v15, v97
	s_add_i32 s0, s46, 1
	v_add_f32_e32 v96, v15, v0
	s_cmp_lg_u32 s46, 2
	s_cselect_b32 s46, s0, 0
	v_lshl_add_u32 v252, s46, 14, v216
	v_add_u32_e32 v253, v252, v191
	v_add_u32_e32 v252, v252, v218
	v_mfma_f32_32x32x16_bf16 v[64:79], v[136:139], v[156:159], v[64:79]
	v_exp_f32_e32 v156, v98
	v_exp_f32_e32 v157, v99
	v_add_f32_e32 v96, v156, v96
	v_add_f32_e32 v96, v157, v96
	ds_read_b128 v[172:175], v253
	ds_read_b128 v[176:179], v252
	ds_read_b128 v[168:171], v253 offset:4096
	ds_read_b128 v[164:167], v252 offset:4096
	v_mfma_f32_32x32x16_bf16 v[64:79], v[116:119], v[152:155], v[64:79]
	v_exp_f32_e32 v158, v100
	v_exp_f32_e32 v159, v101
	v_add_f32_e32 v96, v158, v96
	v_add_f32_e32 v96, v159, v96
	v_mfma_f32_32x32x16_bf16 v[64:79], v[112:115], v[148:151], v[64:79]
	v_exp_f32_e32 v160, v102
	v_exp_f32_e32 v161, v103
	v_add_f32_e32 v162, v160, v96
	ds_read_b64_tr_b16 v[96:97], v234 offset:8192
	ds_read_b64_tr_b16 v[98:99], v234 offset:8704
	ds_read_b64_tr_b16 v[100:101], v234 offset:9216
	ds_read_b64_tr_b16 v[102:103], v234 offset:9728
	ds_read_b64_tr_b16 v[148:149], v234 offset:10240
	ds_read_b64_tr_b16 v[150:151], v234 offset:10752
	ds_read_b64_tr_b16 v[152:153], v234 offset:11264
	ds_read_b64_tr_b16 v[154:155], v234 offset:11776
	v_add_f32_e32 v162, v161, v162
	v_mfma_f32_32x32x16_bf16 v[48:63], v[140:143], v[144:147], v[48:63]
	v_exp_f32_e32 v144, v104
	v_exp_f32_e32 v145, v105
	v_add_f32_e32 v104, v144, v162
	v_add_f32_e32 v104, v145, v104
	v_mfma_f32_32x32x16_bf16 v[48:63], v[136:139], v[10:13], v[48:63]
	v_exp_f32_e32 v146, v106
	v_exp_f32_e32 v147, v107
	v_add_f32_e32 v10, v146, v104
	v_add_f32_e32 v10, v147, v10
	v_mfma_f32_32x32x16_bf16 v[48:63], v[116:119], v[6:9], v[48:63]
	v_exp_f32_e32 v108, v108
	v_exp_f32_e32 v109, v109
	v_add_f32_e32 v6, v108, v10
	v_add_f32_e32 v6, v109, v6
	v_mfma_f32_32x32x16_bf16 v[48:63], v[112:115], v[2:5], v[48:63]
	v_exp_f32_e32 v110, v110
	v_exp_f32_e32 v111, v111
	v_add_f32_e32 v162, v110, v6
	ds_read_b64_tr_b16 v[2:3], v234 offset:12288
	ds_read_b64_tr_b16 v[4:5], v234 offset:12800
	ds_read_b64_tr_b16 v[6:7], v234 offset:13312
	ds_read_b64_tr_b16 v[8:9], v234 offset:13824
	ds_read_b64_tr_b16 v[10:11], v234 offset:14336
	ds_read_b64_tr_b16 v[12:13], v234 offset:14848
	ds_read_b64_tr_b16 v[104:105], v234 offset:15360
	ds_read_b64_tr_b16 v[106:107], v234 offset:15872
	s_waitcnt lgkmcnt(8)
	v_add_f32_e32 v162, v111, v162
	v_mfma_f32_32x32x16_bf16 v[32:47], v[140:143], v[96:99], v[32:47]
	v_exp_f32_e32 v80, v80
	v_exp_f32_e32 v81, v81
	v_add_f32_e32 v96, v80, v162
	v_add_f32_e32 v96, v81, v96
	v_mfma_f32_32x32x16_bf16 v[32:47], v[136:139], v[100:103], v[32:47]
	v_exp_f32_e32 v82, v82
	v_exp_f32_e32 v83, v83
	v_add_f32_e32 v96, v82, v96
	v_add_f32_e32 v96, v83, v96
	v_mfma_f32_32x32x16_bf16 v[32:47], v[116:119], v[148:151], v[32:47]
	v_exp_f32_e32 v84, v84
	v_exp_f32_e32 v85, v85
	v_add_f32_e32 v96, v84, v96
	v_add_f32_e32 v96, v85, v96
	v_mfma_f32_32x32x16_bf16 v[32:47], v[112:115], v[152:155], v[32:47]
	v_exp_f32_e32 v86, v86
	v_exp_f32_e32 v87, v87
	v_add_f32_e32 v96, v86, v96
	v_add_f32_e32 v96, v87, v96
	s_waitcnt lgkmcnt(0)
	v_mfma_f32_32x32x16_bf16 v[16:31], v[140:143], v[2:5], v[16:31]
	v_exp_f32_e32 v2, v88
	v_exp_f32_e32 v3, v89
	v_add_f32_e32 v4, v2, v96
	v_add_f32_e32 v4, v3, v4
	v_mfma_f32_32x32x16_bf16 v[16:31], v[136:139], v[6:9], v[16:31]
	v_exp_f32_e32 v5, v90
	v_exp_f32_e32 v6, v91
	v_add_f32_e32 v4, v5, v4
	v_add_f32_e32 v4, v6, v4
	v_mfma_f32_32x32x16_bf16 v[16:31], v[116:119], v[10:13], v[16:31]
	v_exp_f32_e32 v7, v92
	v_exp_f32_e32 v8, v93
	v_add_f32_e32 v4, v7, v4
	v_add_f32_e32 v4, v8, v4
	v_mfma_f32_32x32x16_bf16 v[16:31], v[112:115], v[104:107], v[16:31]
	v_exp_f32_e32 v9, v94
	v_exp_f32_e32 v10, v95
	v_add_f32_e32 v4, v9, v4
	v_add_f32_e32 v4, v10, v4
	s_add_i32 s0, s47, 1
	s_cmp_lg_u32 s47, 2
	s_cselect_b32 s47, s0, 0
	s_and_b32 s21, s16, 0xc000
	s_add_u32 s16, s16, 0x4000
	s_addc_u32 s17, s17, 0
	s_add_i32 s45, s45, 1
	s_add_i32 s44, s44, 64
	v_add_f32_e32 v229, v229, v4
	s_cmp_eq_u32 s41, s44
	s_cbranch_scc1 .LBB0_228
.LBB0_204:
	v_add_u32_e32 v234, s21, v217
	s_add_i32 s0, s40, s44
	s_cmpk_gt_i32 s0, 0x9e
	s_cselect_b32 s20, 2, 1
	s_cmpk_lt_i32 s0, 0xff42
	s_cselect_b64 s[0:1], -1, 0
	s_cmp_lg_u64 s[0:1], 0
	s_subb_u32 s51, s20, 0
	s_cmp_eq_u32 s51, s50
	s_cbranch_scc1 .LBB0_215
	s_cmp_gt_i32 s51, 1
	s_cbranch_scc0 .LBB0_211
	v_mov_b32_e32 v14, s93
	ds_read_b32 v233, v14
	s_cbranch_execz .LBB0_212
	s_branch .LBB0_214

; #define SCHED_FENCE() __builtin_amdgcn_sched_barrier(0)
; __device__ __forceinline__ void da_phase(LAS unsigned char* lds, const bf16* Q, const bf16* Kb, const bf16* Vb, bf16* O, const float* lq1, const float* lk1, const float* lq2, const float* lk2,
;                                          const float* t5, int G, int wave, int lane, int tid) {
;     ...
;             F16 p0, p1;
;             {   typedef float F2i __attribute__((ext_vector_type(2))); F2i c2 = {cbm, cbm}; asm volatile("" : "+v"(c2));
; #pragma unroll
;                 for (int r = 0; r < 16; r += 2) { p0[r] = c2.x; p0[r + 1] = c2.y; p1[r] = c2.x; p1[r + 1] = c2.y; } }
;             asm volatile("s_waitcnt lgkmcnt(15)" ::: "memory"); SCHED_FENCE();
; #pragma unroll
;             for (int d0 = 0; d0 < 4; ++d0) p0 = __builtin_amdgcn_mfma_f32_32x32x16_bf16(__builtin_bit_cast(H8, kf[d0]), qf[d0], p0, 0, 0, 0);
;             SCHED_FENCE();
;             DS_RD128(kf[0], ka0, 2048); DS_RD128(kf[1], ka1, 2048); DS_RD128(kf[2], ka0, 6144); DS_RD128(kf[3], ka1, 6144);
;             if (t + 2 < NT) DA_DMA_K(t + 2, ks_n2);
;             LGKM_WAIT(0); SCHED_FENCE();
;             float a0;
;             p1 = __builtin_amdgcn_mfma_f32_32x32x16_bf16(__builtin_bit_cast(H8, kf[0]), qf[0], p1, 0, 0, 0); a0 = __builtin_fmaxf(__builtin_fmaxf(p0[0], p0[1]), p0[2]); a0 = __builtin_fmaxf(__builtin_fmaxf(a0, p0[3]), p0[4]); asm volatile("" : "+v"(a0)); SCHED_FENCE();
;             p1 = __builtin_amdgcn_mfma_f32_32x32x16_bf16(__builtin_bit_cast(H8, kf[1]), qf[1], p1, 0, 0, 0); a0 = __builtin_fmaxf(__builtin_fmaxf(a0, p0[5]), p0[6]); a0 = __builtin_fmaxf(__builtin_fmaxf(a0, p0[7]), p0[8]); asm volatile("" : "+v"(a0)); SCHED_FENCE();
;             p1 = __builtin_amdgcn_mfma_f32_32x32x16_bf16(__builtin_bit_cast(H8, kf[2]), qf[2], p1, 0, 0, 0); a0 = __builtin_fmaxf(__builtin_fmaxf(a0, p0[9]), p0[10]); a0 = __builtin_fmaxf(__builtin_fmaxf(a0, p0[11]), p0[12]); asm volatile("" : "+v"(a0)); SCHED_FENCE();
;             p1 = __builtin_amdgcn_mfma_f32_32x32x16_bf16(__builtin_bit_cast(H8, kf[3]), qf[3], p1, 0, 0, 0); a0 = __builtin_fmaxf(__builtin_fmaxf(a0, p0[13]), p0[14]); a0 = __builtin_fmaxf(a0, p0[15]); asm volatile("" : "+v"(a0)); SCHED_FENCE();
;             if (t + 2 < NT) DA_DMA_V(t + 2, (t + 2) & 3);
;     ...
;             pw[0] = DA_PACK8(p0, 0); pw[1] = DA_PACK8(p0, 8); pw[2] = DA_PACK8(p1, 0); pw[3] = DA_PACK8(p1, 8);
.LBB0_215:
	v_cvt_pk_bf16_f32 v140, v0, v15
	v_cvt_pk_bf16_f32 v141, v156, v157
	v_cvt_pk_bf16_f32 v142, v158, v159
	v_cvt_pk_bf16_f32 v143, v160, v161
	v_cvt_pk_bf16_f32 v138, v108, v109
	v_cvt_pk_bf16_f32 v139, v110, v111
	v_mfma_f32_32x32x16_bf16 v[96:111], v[172:175], v[120:123], v[236:251]
	v_cvt_pk_bf16_f32 v136, v144, v145
	v_cvt_pk_bf16_f32 v137, v146, v147
	ds_read_b64_tr_b16 v[160:161], v234 offset:0
	ds_read_b64_tr_b16 v[162:163], v234 offset:512
	ds_read_b64_tr_b16 v[156:157], v234 offset:1024
	ds_read_b64_tr_b16 v[158:159], v234 offset:1536
	v_mfma_f32_32x32x16_bf16 v[96:111], v[176:179], v[124:127], v[96:111]
	v_cvt_pk_bf16_f32 v116, v80, v81
	v_cvt_pk_bf16_f32 v117, v82, v83
	v_cvt_pk_bf16_f32 v118, v84, v85
	v_cvt_pk_bf16_f32 v119, v86, v87
	ds_read_b64_tr_b16 v[152:153], v234 offset:2048
	ds_read_b64_tr_b16 v[154:155], v234 offset:2560
	ds_read_b64_tr_b16 v[148:149], v234 offset:3072
	ds_read_b64_tr_b16 v[150:151], v234 offset:3584
	v_mfma_f32_32x32x16_bf16 v[96:111], v[168:171], v[128:131], v[96:111]
	v_cvt_pk_bf16_f32 v112, v2, v3
	v_cvt_pk_bf16_f32 v113, v5, v6
	v_cvt_pk_bf16_f32 v114, v7, v8
	v_cvt_pk_bf16_f32 v115, v9, v10
	ds_read_b64_tr_b16 v[144:145], v234 offset:4096
	ds_read_b64_tr_b16 v[146:147], v234 offset:4608
	ds_read_b64_tr_b16 v[10:11], v234 offset:5120
	ds_read_b64_tr_b16 v[12:13], v234 offset:5632
	v_mfma_f32_32x32x16_bf16 v[96:111], v[164:167], v[132:135], v[96:111]
	ds_read_b64_tr_b16 v[6:7], v234 offset:6144
	ds_read_b64_tr_b16 v[8:9], v234 offset:6656
	ds_read_b64_tr_b16 v[2:3], v234 offset:7168
	ds_read_b64_tr_b16 v[4:5], v234 offset:7680
	ds_read_b128 v[176:179], v253 offset:2048
	ds_read_b128 v[172:175], v252 offset:2048
	ds_read_b128 v[168:171], v253 offset:6144
	ds_read_b128 v[164:167], v252 offset:6144
	s_cmp_ge_u32 s45, s39
	s_cbranch_scc1 .LBB0_217
	v_lshl_add_u64 v[182:183], v[204:205], 0, s[16:17]
	s_mov_b64 s[0:1], 0x1b208000
	v_lshl_add_u64 v[184:185], v[182:183], 0, s[0:1]
	s_lshl_b32 s0, s47, 14
	s_add_i32 s68, s3, s0
	s_mov_b64 s[0:1], 0x1b209000
	v_lshl_add_u64 v[182:183], v[182:183], 0, s[0:1]
	s_add_i32 s0, s68, 0x400
	s_mov_b32 m0, s68
	s_nop 0
	global_load_lds_dwordx4 v[184:185], off
	s_mov_b32 m0, s0
	s_nop 0
	global_load_lds_dwordx4 v[182:183], off
.LBB0_217:
	s_waitcnt lgkmcnt(0)
	v_mfma_f32_32x32x16_bf16 v[80:95], v[176:179], v[120:123], v[236:251]
	v_max3_f32 v0, v96, v97, v98
	v_max3_f32 v0, v0, v99, v100
	v_mfma_f32_32x32x16_bf16 v[80:95], v[172:175], v[124:127], v[80:95]
	v_max3_f32 v0, v0, v101, v102
	v_max3_f32 v0, v0, v103, v104
	v_mfma_f32_32x32x16_bf16 v[80:95], v[168:171], v[128:131], v[80:95]
	v_max3_f32 v0, v0, v105, v106
	v_max3_f32 v0, v0, v107, v108
	v_mfma_f32_32x32x16_bf16 v[80:95], v[164:167], v[132:135], v[80:95]
	v_max_f32_e32 v0, v0, v0
	v_max_f32_e32 v15, v109, v109
	v_max_f32_e32 v0, v0, v15
	v_max3_f32 v0, v0, v110, v111
	s_cmp_gt_u32 s45, s39
	s_cbranch_scc1 .Lda_vskip
	v_lshl_add_u64 v[164:165], v[202:203], 0, s[16:17]
	s_mov_b64 s[0:1], 0x27204000
	v_lshl_add_u64 v[166:167], v[164:165], 0, s[0:1]
	s_add_i32 s0, s16, 0x4000
	s_and_b32 s0, s0, 0xc000
	s_add_i32 s20, s3, s0
	s_add_i32 m0, s20, 0xc000
	s_mov_b64 s[0:1], 0x27205000
	s_add_i32 s20, s20, 0xc400
	v_lshl_add_u64 v[164:165], v[164:165], 0, s[0:1]
	global_load_lds_dwordx4 v[166:167], off
	s_mov_b32 m0, s20
	s_nop 0
	global_load_lds_dwordx4 v[164:165], off

; __device__ __forceinline__ int crow(int r, int hi) { return (r & 3) + 8 * (r >> 2) + 4 * hi; }
; __device__ __forceinline__ unsigned cvtpk(float lo, float hi) { f32x2_t v = {lo, hi}; bf16x2_t b = __builtin_convertvector(v, bf16x2_t); return __builtin_bit_cast(unsigned, b); }
; __device__ __forceinline__ float half_swap_max(float v) { auto rr = __builtin_amdgcn_permlane32_swap(__float_as_uint(v), __float_as_uint(v), false, false); return fmaxf(__uint_as_float(rr[0]), __uint_as_float(rr[1])); }
; __device__ __forceinline__ void da_phase(LAS unsigned char* lds, const bf16* Q, const bf16* Kb, const bf16* Vb, bf16* O, const float* lq1, const float* lk1, const float* lq2, const float* lk2,
;                                          const float* t5, int G, int wave, int lane, int tid) {
;     ...
;             float a1 = __builtin_fmaxf(__builtin_fmaxf(p1[0], p1[1]), p1[2]);
; #pragma unroll
;             for (int r = 3; r < 15; r += 2) a1 = __builtin_fmaxf(__builtin_fmaxf(a1, p1[r]), p1[r + 1]);
;             a1 = __builtin_fmaxf(a1, p1[15]);
;             const float rml = __builtin_fmaxf(a0, a1);
;             if (t == 0 || __any(rml > 8.0f)) {
;                 const float rm = half_swap_max(rml);
;                 const float dl = (t == 0) ? rm : __builtin_fmaxf(rm, 0.f); m += dl;
; #pragma unroll
;                 for (int r = 0; r < 16; ++r) { p0[r] -= dl; p1[r] -= dl; }
;                 cbm = cb - m;
;                 const float f = __builtin_amdgcn_exp2f(-dl); l *= f;
; #pragma unroll
;                 for (int k = 0; k < 4; ++k)
; #pragma unroll
;                     for (int e = 0; e < 4; ++e) { const unsigned w = pw[k][e]; pw[k][e] = cvtpk(__uint_as_float(w << 16) * f, __uint_as_float(w & 0xffff0000u) * f); }
;                 if (hi == 0) wsf[r32] = f;
; #pragma unroll
;                 for (int r = 0; r < 16; ++r) { const float fr = wsf[crow(r, hi)];
; #pragma unroll
;                     for (int db = 0; db < 4; ++db) o[db][r] *= fr; }
;             }
;     ...
;         {   const unsigned vaddr = ldsb + VS + ((NT - 1) & 3) * 16384 + vlane; DA_VREADS(va, vaddr, 0); DA_VREADS(vb, vaddr, 1); da_pv(o, pw, va, vb, vaddr); }
;     ...
;         int lane_e = lane; asm volatile("" : "+v"(lane_e));
;         const int r32e = lane_e & 31, hie = lane_e >> 5;
;         const float lt = half_swap_sum(l);
;         if (hie == 0) wsf[r32e] = (comp == 0 ? 1.0f : -lam) / lt;
.LBB0_221:
	v_max3_f32 v15, v80, v81, v82
	v_max3_f32 v15, v15, v83, v84
	v_max3_f32 v15, v15, v85, v86
	v_max3_f32 v15, v15, v87, v88
	v_max3_f32 v15, v15, v89, v90
	v_max3_f32 v15, v15, v91, v92
	v_max3_f32 v15, v15, v93, v94
	v_max3_f32 v0, v0, v15, v95
	v_cmp_lt_f32_e32 vcc, s18, v0
	s_cmp_eq_u64 vcc, 0
	s_cbranch_scc1 .LBB0_203
.Lda_rare:
	s_mov_b32 s18, 0x41000000
	s_cmp_eq_u32 s44, 0
	s_cselect_b64 s[10:11], -1, 0
	v_mov_b32_e32 v14, v0
	s_nop 1
	v_permlane32_swap_b32_e32 v0, v14
	v_max_f32_e32 v14, v14, v14
	v_max_f32_e32 v0, v0, v0
	v_max_f32_e32 v0, v0, v14
	v_max_f32_e32 v14, 0, v0
	v_cndmask_b32_e64 v14, v14, v0, s[10:11]
	v_exp_f32_e64 v0, -v14
	s_and_saveexec_b64 s[0:1], s[4:5]
	s_cbranch_execz .LBB0_202
	ds_write_b32 v220, v0
	s_branch .LBB0_202
.LBB0_228:
	v_cvt_pk_bf16_f32 v140, v0, v15
	v_cvt_pk_bf16_f32 v141, v156, v157
	v_cvt_pk_bf16_f32 v142, v158, v159
	v_cvt_pk_bf16_f32 v143, v160, v161
	v_cvt_pk_bf16_f32 v136, v144, v145
	v_cvt_pk_bf16_f32 v137, v146, v147
	v_cvt_pk_bf16_f32 v138, v108, v109
	v_cvt_pk_bf16_f32 v139, v110, v111
	v_cvt_pk_bf16_f32 v116, v80, v81
	v_cvt_pk_bf16_f32 v117, v82, v83
	v_cvt_pk_bf16_f32 v118, v84, v85
	v_cvt_pk_bf16_f32 v119, v86, v87
	v_cvt_pk_bf16_f32 v112, v2, v3
	v_cvt_pk_bf16_f32 v113, v5, v6
	v_cvt_pk_bf16_f32 v114, v7, v8
	v_cvt_pk_bf16_f32 v115, v9, v10
	ds_read_b64_tr_b16 v[2:3], v221 offset:0
	ds_read_b64_tr_b16 v[4:5], v221 offset:512
	ds_read_b64_tr_b16 v[6:7], v221 offset:1024
	ds_read_b64_tr_b16 v[8:9], v221 offset:1536
	ds_read_b64_tr_b16 v[10:11], v221 offset:2048
	ds_read_b64_tr_b16 v[12:13], v221 offset:2560
	ds_read_b64_tr_b16 v[80:81], v221 offset:3072
	ds_read_b64_tr_b16 v[82:83], v221 offset:3584
	ds_read_b64_tr_b16 v[84:85], v221 offset:4096
	ds_read_b64_tr_b16 v[86:87], v221 offset:4608
	ds_read_b64_tr_b16 v[88:89], v221 offset:5120
	ds_read_b64_tr_b16 v[90:91], v221 offset:5632
	ds_read_b64_tr_b16 v[92:93], v221 offset:6144
	ds_read_b64_tr_b16 v[94:95], v221 offset:6656
	ds_read_b64_tr_b16 v[96:97], v221 offset:7168
	ds_read_b64_tr_b16 v[98:99], v221 offset:7680
	s_waitcnt lgkmcnt(0)
	s_nop 0
	v_mfma_f32_32x32x16_bf16 v[64:79], v[140:143], v[2:5], v[64:79]
	v_mfma_f32_32x32x16_bf16 v[64:79], v[136:139], v[6:9], v[64:79]
	v_mfma_f32_32x32x16_bf16 v[64:79], v[116:119], v[10:13], v[64:79]
	v_mfma_f32_32x32x16_bf16 v[64:79], v[112:115], v[80:83], v[64:79]
	ds_read_b64_tr_b16 v[2:3], v221 offset:8192
	ds_read_b64_tr_b16 v[4:5], v221 offset:8704
	ds_read_b64_tr_b16 v[6:7], v221 offset:9216
	ds_read_b64_tr_b16 v[8:9], v221 offset:9728
	ds_read_b64_tr_b16 v[10:11], v221 offset:10240
	ds_read_b64_tr_b16 v[12:13], v221 offset:10752
	ds_read_b64_tr_b16 v[80:81], v221 offset:11264
	ds_read_b64_tr_b16 v[82:83], v221 offset:11776
	v_mfma_f32_32x32x16_bf16 v[48:63], v[140:143], v[84:87], v[48:63]
	v_mfma_f32_32x32x16_bf16 v[48:63], v[136:139], v[88:91], v[48:63]
	v_mfma_f32_32x32x16_bf16 v[48:63], v[116:119], v[92:95], v[48:63]
	v_mfma_f32_32x32x16_bf16 v[48:63], v[112:115], v[96:99], v[48:63]
	ds_read_b64_tr_b16 v[84:85], v221 offset:12288
	ds_read_b64_tr_b16 v[86:87], v221 offset:12800
	ds_read_b64_tr_b16 v[88:89], v221 offset:13312
	ds_read_b64_tr_b16 v[90:91], v221 offset:13824
	ds_read_b64_tr_b16 v[92:93], v221 offset:14336
	ds_read_b64_tr_b16 v[94:95], v221 offset:14848
	ds_read_b64_tr_b16 v[96:97], v221 offset:15360
	ds_read_b64_tr_b16 v[98:99], v221 offset:15872
	s_waitcnt lgkmcnt(8)
	v_mfma_f32_32x32x16_bf16 v[32:47], v[140:143], v[2:5], v[32:47]
	v_mfma_f32_32x32x16_bf16 v[32:47], v[136:139], v[6:9], v[32:47]
	v_mfma_f32_32x32x16_bf16 v[32:47], v[116:119], v[10:13], v[32:47]
	v_mfma_f32_32x32x16_bf16 v[32:47], v[112:115], v[80:83], v[32:47]
	s_waitcnt lgkmcnt(0)
	v_mfma_f32_32x32x16_bf16 v[16:31], v[140:143], v[84:87], v[16:31]
	v_mfma_f32_32x32x16_bf16 v[16:31], v[136:139], v[88:91], v[16:31]
	v_mfma_f32_32x32x16_bf16 v[16:31], v[116:119], v[92:95], v[16:31]
	v_mfma_f32_32x32x16_bf16 v[16:31], v[112:115], v[96:99], v[16:31]
	v_mov_b32_e32 v0, v206
	v_mov_b32_e32 v2, v229
	s_nop 1
	v_permlane32_swap_b32_e32 v229, v2
	v_and_b32_e32 v126, 31, v0
	v_cmp_gt_u32_e32 vcc, 32, v0
	s_and_saveexec_b64 s[0:1], vcc
	s_cbranch_execz .LBB0_230
	v_add_f32_e32 v2, v229, v2
	v_div_scale_f32 v3, s[10:11], v2, v2, v222
	v_rcp_f32_e32 v4, v3
	v_div_scale_f32 v5, vcc, v222, v2, v222
	v_fma_f32 v6, -v3, v4, 1.0
	v_fmac_f32_e32 v4, v6, v4
	v_mul_f32_e32 v6, v5, v4
	v_fma_f32 v7, -v3, v6, v5
	v_fmac_f32_e32 v6, v7, v4
	v_fma_f32 v3, -v3, v6, v5
	v_div_fmas_f32 v3, v3, v4, v6
	v_div_fixup_f32 v2, v3, v2, v222
	v_lshl_add_u32 v3, v126, 2, s99
	ds_write_b32 v3, v2
